# v8 plus the LDS-staged sliding-window scan, now guarded by grid size (original scan kept for any grid other than 256)
# baseline (speedup 1.0000x reference)
; __device__ __forceinline__ void scan_phase(bf16* U, bf16* So, const float* DEC, int bid, int G, int tid) {
;     if (tid >= 256) return;
;     for (int e = bid * 256 + tid; e < NH * HV * (HK / 2); e += G * 256) {
;         const int hd = e >> 14, rem = e & 16383, v = rem >> 6, kp = rem & 63;
;         unsigned* up = (unsigned*)(U + ((size_t)hd * HV + v) * HK + 2 * kp);
;         unsigned* op = (unsigned*)(So + ((size_t)hd * HV + v) * HK + 2 * kp);
;         const f32x2* dp = (const f32x2*)(DEC + hd * HK + 2 * kp);
; __global__ void __launch_bounds__(NTHR, 2) fwd_megakernel(Args a) {
;     ...
;                 { PHASE_IDS if (tid < 256) scan_phase(Ub, Ub, DEC, bid, G, tid); else conv_phase(PROJ, a.in[7] + (size_t)l * 3 * DCONV, Yb, bid * 256 + (tid - 256), G * 256); }
.LBB0_480:
	s_or_b64 exec, exec, s[2:3]
	s_waitcnt vmcnt(22) lgkmcnt(0)
	v_mov_b32_e32 v4, v168
	s_movk_i32 s2, 0xff
	s_barrier
	s_cmp_lg_u32 s82, 0x100
	s_cbranch_scc1 .Lscan_nopre
	v_readfirstlane_b32 s27, v168
	s_lshr_b32 s32, s18, 6
	s_lshl_b32 s32, s32, 9
	s_lshr_b32 s27, s27, 6
	s_lshl_b32 s38, s27, 16
	s_add_u32 s32, s32, s38
	s_add_u32 s38, s80, 0x24e00000
	s_addc_u32 s39, s81, 0
	s_add_u32 s38, s38, s32
	s_addc_u32 s39, s39, 0
	v_and_b32_e32 v6, 63, v168
	v_lshrrev_b32_e32 v7, 5, v6
	v_and_b32_e32 v6, 31, v6
	v_lshlrev_b32_e32 v6, 4, v6
	v_lshl_add_u32 v6, v7, 11, v6
	s_lshl_b32 s27, s27, 14
	s_add_i32 m0, s27, 0x0
	s_nop 0
	global_load_lds_dwordx4 v6, s[38:39]
	s_add_u32 s38, s38, 0x1000
	s_addc_u32 s39, s39, 0
	s_add_i32 m0, s27, 0x400
	s_nop 0
	global_load_lds_dwordx4 v6, s[38:39]
	s_add_u32 s38, s38, 0x1000
	s_addc_u32 s39, s39, 0
	s_add_i32 m0, s27, 0x800
	s_nop 0
	global_load_lds_dwordx4 v6, s[38:39]
	s_add_u32 s38, s38, 0x1000
	s_addc_u32 s39, s39, 0
	s_add_i32 m0, s27, 0xc00
	s_nop 0
	global_load_lds_dwordx4 v6, s[38:39]
	s_add_u32 s38, s38, 0x1000
	s_addc_u32 s39, s39, 0
	s_add_i32 m0, s27, 0x1000
	s_nop 0
	global_load_lds_dwordx4 v6, s[38:39]
	s_add_u32 s38, s38, 0x1000
	s_addc_u32 s39, s39, 0
	s_add_i32 m0, s27, 0x1400
	s_nop 0
	global_load_lds_dwordx4 v6, s[38:39]
	s_add_u32 s38, s38, 0x1000
	s_addc_u32 s39, s39, 0
	s_add_i32 m0, s27, 0x1800
	s_nop 0
	global_load_lds_dwordx4 v6, s[38:39]
	s_add_u32 s38, s38, 0x1000
	s_addc_u32 s39, s39, 0
	s_add_i32 m0, s27, 0x1c00
	s_nop 0
	global_load_lds_dwordx4 v6, s[38:39]
	s_add_u32 s38, s38, 0x1000
	s_addc_u32 s39, s39, 0
	s_add_i32 m0, s27, 0x2000
	s_nop 0
	global_load_lds_dwordx4 v6, s[38:39]
	s_add_u32 s38, s38, 0x1000
	s_addc_u32 s39, s39, 0
	s_add_i32 m0, s27, 0x2400
	s_nop 0
	global_load_lds_dwordx4 v6, s[38:39]
	s_add_u32 s38, s38, 0x1000
	s_addc_u32 s39, s39, 0
	s_add_i32 m0, s27, 0x2800
	s_nop 0
	global_load_lds_dwordx4 v6, s[38:39]
	s_add_u32 s38, s38, 0x1000
	s_addc_u32 s39, s39, 0
	s_add_i32 m0, s27, 0x2c00
	s_nop 0
	global_load_lds_dwordx4 v6, s[38:39]
	s_add_u32 s38, s38, 0x1000
	s_addc_u32 s39, s39, 0
	s_add_i32 m0, s27, 0x3000
	s_nop 0
	global_load_lds_dwordx4 v6, s[38:39]
	s_add_u32 s38, s38, 0x1000
	s_addc_u32 s39, s39, 0
	s_add_i32 m0, s27, 0x3400
	s_nop 0
	global_load_lds_dwordx4 v6, s[38:39]
	s_add_u32 s38, s38, 0x1000
	s_addc_u32 s39, s39, 0
	s_add_i32 m0, s27, 0x3800
	s_nop 0
	global_load_lds_dwordx4 v6, s[38:39]
	s_add_u32 s38, s38, 0x1000
	s_addc_u32 s39, s39, 0
	s_add_i32 m0, s27, 0x3c00
	s_nop 0
	global_load_lds_dwordx4 v6, s[38:39]
	s_waitcnt vmcnt(0)
	s_barrier
.Lscan_nopre:
	s_nop 0
	v_cmp_lt_i32_e32 vcc, s2, v4
	s_and_saveexec_b64 s[2:3], vcc
	s_xor_b64 s[44:45], exec, s[2:3]
	s_cbranch_execz .LBB0_489
	v_readlane_b32 s2, v249, 62
	s_nop 1
	v_add_u32_e32 v74, s2, v4
	s_mov_b32 s2, 0x20000
	v_cmp_gt_i32_e32 vcc, s2, v74
	s_and_saveexec_b64 s[46:47], vcc
	s_cbranch_execz .LBB0_488
	v_lshlrev_b32_e32 v75, 3, v74
	s_mov_b64 s[48:49], 0

; __device__ __forceinline__ float bflo(unsigned u) { return __uint_as_float(u << 16); }
; __device__ __forceinline__ float bfhi(unsigned u) { return __uint_as_float(u & 0xffff0000u); }
; __device__ __forceinline__ unsigned pk2(float lo, float hi) { return pg8::cvt_pk_bf16(lo, hi); }
; __device__ __forceinline__ void scan_phase(bf16* U, bf16* So, const float* DEC, int bid, int G, int tid) {
;     ...
;     for (int e = bid * 256 + tid; e < NH * HV * (HK / 2); e += G * 256) {
;         const int hd = e >> 14, rem = e & 16383, v = rem >> 6, kp = rem & 63;
;         unsigned* up = (unsigned*)(U + ((size_t)hd * HV + v) * HK + 2 * kp);
;         unsigned* op = (unsigned*)(So + ((size_t)hd * HV + v) * HK + 2 * kp);
;         const f32x2* dp = (const f32x2*)(DEC + hd * HK + 2 * kp);
;         float s0 = 0.f, s1 = 0.f;
;         for (int c0 = 0; c0 < NCH; c0 += SCAN_B) {
;             unsigned ub[SCAN_B]; f32x2 db[SCAN_B];
; #pragma unroll
;             for (int i = 0; i < SCAN_B; ++i) { ub[i] = up[(size_t)(c0 + i) * (NH * HV * HK / 2)]; db[i] = dp[(size_t)(c0 + i) * (DQK / 2)]; }
; #pragma unroll
;             for (int i = 0; i < SCAN_B; ++i) { op[(size_t)(c0 + i) * (NH * HV * HK / 2)] = pk2(s0, s1); s0 = db[i].x * s0 + bflo(ub[i]); s1 = db[i].y * s1 + bfhi(ub[i]); }
; __global__ void __launch_bounds__(NTHR, 2) fwd_megakernel(Args a) {
;     ...
;                 { PHASE_IDS if (tid < 256) scan_phase(Ub, Ub, DEC, bid, G, tid); else conv_phase(PROJ, a.in[7] + (size_t)l * 3 * DCONV, Yb, bid * 256 + (tid - 256), G * 256); }
.LBB0_489:
	s_andn2_saveexec_b64 s[2:3], s[44:45]
	s_cbranch_execz .LBB0_496
	v_readlane_b32 s4, v249, 61
	s_nop 1
	v_add_u32_e32 v100, s4, v4
	s_mov_b32 s4, 0x10000
	v_cmp_gt_i32_e32 vcc, s4, v100
	s_and_saveexec_b64 s[4:5], vcc
	s_cbranch_execz .LBB0_495
	s_cmp_lg_u32 s82, 0x100
	s_cbranch_scc1 .Lscan_orig
	v_readfirstlane_b32 s27, v168
	s_lshl_b32 s32, s18, 2
	s_lshr_b32 s27, s27, 6
	s_add_u32 s27, s27, s32
	s_lshl_b32 s27, s27, 8
	v_and_b32_e32 v11, 63, v168
	v_lshl_add_u32 v10, v11, 2, s27
	v_lshlrev_b32_e32 v11, 3, v11
	s_add_u32 s52, s80, 0x1ee00000
	s_addc_u32 s53, s81, 0
	s_mov_b64 s[54:55], s[52:53]
	v_mov_b32_e32 v8, 0
	v_mov_b32_e32 v9, 0
	global_load_dword v20, v10, s[52:53]
	s_add_u32 s52, s52, 0x40000
	s_addc_u32 s53, s53, 0
	global_load_dword v21, v10, s[52:53]
	s_add_u32 s52, s52, 0x40000
	s_addc_u32 s53, s53, 0
	global_load_dword v22, v10, s[52:53]
	s_add_u32 s52, s52, 0x40000
	s_addc_u32 s53, s53, 0
	global_load_dword v23, v10, s[52:53]
	s_add_u32 s52, s52, 0x40000
	s_addc_u32 s53, s53, 0
	global_load_dword v24, v10, s[52:53]
	s_add_u32 s52, s52, 0x40000
	s_addc_u32 s53, s53, 0
	global_load_dword v25, v10, s[52:53]
	s_add_u32 s52, s52, 0x40000
	s_addc_u32 s53, s53, 0
	global_load_dword v26, v10, s[52:53]
	s_add_u32 s52, s52, 0x40000
	s_addc_u32 s53, s53, 0
	global_load_dword v27, v10, s[52:53]
	s_add_u32 s52, s52, 0x40000
	s_addc_u32 s53, s53, 0
	global_load_dword v28, v10, s[52:53]
	s_add_u32 s52, s52, 0x40000
	s_addc_u32 s53, s53, 0
	global_load_dword v29, v10, s[52:53]
	s_add_u32 s52, s52, 0x40000
	s_addc_u32 s53, s53, 0
	global_load_dword v30, v10, s[52:53]
	s_add_u32 s52, s52, 0x40000
	s_addc_u32 s53, s53, 0
	global_load_dword v31, v10, s[52:53]
	s_add_u32 s52, s52, 0x40000
	s_addc_u32 s53, s53, 0
	global_load_dword v32, v10, s[52:53]
	s_add_u32 s52, s52, 0x40000
	s_addc_u32 s53, s53, 0
	global_load_dword v33, v10, s[52:53]
	s_add_u32 s52, s52, 0x40000
	s_addc_u32 s53, s53, 0
	global_load_dword v34, v10, s[52:53]
	s_add_u32 s52, s52, 0x40000
	s_addc_u32 s53, s53, 0
	global_load_dword v35, v10, s[52:53]
	s_add_u32 s52, s52, 0x40000
	s_addc_u32 s53, s53, 0
	global_load_dword v36, v10, s[52:53]
	s_add_u32 s52, s52, 0x40000
	s_addc_u32 s53, s53, 0
	global_load_dword v37, v10, s[52:53]
	s_add_u32 s52, s52, 0x40000
	s_addc_u32 s53, s53, 0
	global_load_dword v38, v10, s[52:53]
	s_add_u32 s52, s52, 0x40000
	s_addc_u32 s53, s53, 0
	global_load_dword v39, v10, s[52:53]
	s_add_u32 s52, s52, 0x40000
	s_addc_u32 s53, s53, 0
	global_load_dword v40, v10, s[52:53]
	s_add_u32 s52, s52, 0x40000
	s_addc_u32 s53, s53, 0
	global_load_dword v41, v10, s[52:53]
	s_add_u32 s52, s52, 0x40000
	s_addc_u32 s53, s53, 0
	global_load_dword v42, v10, s[52:53]
	s_add_u32 s52, s52, 0x40000
	s_addc_u32 s53, s53, 0
	global_load_dword v43, v10, s[52:53]
	s_add_u32 s52, s52, 0x40000
	s_addc_u32 s53, s53, 0
	global_load_dword v44, v10, s[52:53]
	s_add_u32 s52, s52, 0x40000
	s_addc_u32 s53, s53, 0
	global_load_dword v45, v10, s[52:53]
	s_add_u32 s52, s52, 0x40000
	s_addc_u32 s53, s53, 0
	global_load_dword v46, v10, s[52:53]
	s_add_u32 s52, s52, 0x40000
	s_addc_u32 s53, s53, 0
	global_load_dword v47, v10, s[52:53]
	s_add_u32 s52, s52, 0x40000
	s_addc_u32 s53, s53, 0
	global_load_dword v48, v10, s[52:53]
	s_add_u32 s52, s52, 0x40000
	s_addc_u32 s53, s53, 0
	global_load_dword v49, v10, s[52:53]
	s_add_u32 s52, s52, 0x40000
	s_addc_u32 s53, s53, 0
	global_load_dword v50, v10, s[52:53]
	s_add_u32 s52, s52, 0x40000
	s_addc_u32 s53, s53, 0
	global_load_dword v51, v10, s[52:53]
	s_add_u32 s52, s52, 0x40000
	s_addc_u32 s53, s53, 0
	ds_read_b64 v[52:53], v11 offset:0
	ds_read_b64 v[54:55], v11 offset:512
	ds_read_b64 v[56:57], v11 offset:1024
	ds_read_b64 v[58:59], v11 offset:1536
	ds_read_b64 v[60:61], v11 offset:2048
	ds_read_b64 v[62:63], v11 offset:2560
	ds_read_b64 v[64:65], v11 offset:3072
	ds_read_b64 v[66:67], v11 offset:3584
	s_waitcnt lgkmcnt(0)
	ds_read_b64 v[68:69], v11 offset:4096
	ds_read_b64 v[70:71], v11 offset:4608
	ds_read_b64 v[72:73], v11 offset:5120
	ds_read_b64 v[74:75], v11 offset:5632
	ds_read_b64 v[76:77], v11 offset:6144
	ds_read_b64 v[78:79], v11 offset:6656
	ds_read_b64 v[80:81], v11 offset:7168
	ds_read_b64 v[82:83], v11 offset:7680
	s_waitcnt vmcnt(31)
	v_cvt_pk_bf16_f32 v12, v8, v9
	global_store_dword v10, v12, s[54:55]
	s_add_u32 s54, s54, 0x40000
	s_addc_u32 s55, s55, 0
	v_lshlrev_b32_e32 v14, 16, v20
	v_and_b32_e32 v15, 0xffff0000, v20
	global_load_dword v20, v10, s[52:53]
	s_add_u32 s52, s52, 0x40000
	s_addc_u32 s53, s53, 0
	v_pk_fma_f32 v[8:9], v[8:9], v[52:53], v[14:15]
	s_waitcnt vmcnt(32)
	v_cvt_pk_bf16_f32 v13, v8, v9
	global_store_dword v10, v13, s[54:55]
	s_add_u32 s54, s54, 0x40000
	s_addc_u32 s55, s55, 0
	v_lshlrev_b32_e32 v14, 16, v21
	v_and_b32_e32 v15, 0xffff0000, v21
	global_load_dword v21, v10, s[52:53]
	s_add_u32 s52, s52, 0x40000
	s_addc_u32 s53, s53, 0
	v_pk_fma_f32 v[8:9], v[8:9], v[54:55], v[14:15]
	s_waitcnt vmcnt(33)
	v_cvt_pk_bf16_f32 v12, v8, v9
	global_store_dword v10, v12, s[54:55]
	s_add_u32 s54, s54, 0x40000
	s_addc_u32 s55, s55, 0
	v_lshlrev_b32_e32 v14, 16, v22
	v_and_b32_e32 v15, 0xffff0000, v22
	global_load_dword v22, v10, s[52:53]
	s_add_u32 s52, s52, 0x40000
	s_addc_u32 s53, s53, 0
	v_pk_fma_f32 v[8:9], v[8:9], v[56:57], v[14:15]
	s_waitcnt vmcnt(34)
	v_cvt_pk_bf16_f32 v13, v8, v9
	global_store_dword v10, v13, s[54:55]
	s_add_u32 s54, s54, 0x40000
	s_addc_u32 s55, s55, 0
	v_lshlrev_b32_e32 v14, 16, v23
	v_and_b32_e32 v15, 0xffff0000, v23
	global_load_dword v23, v10, s[52:53]
	s_add_u32 s52, s52, 0x40000
	s_addc_u32 s53, s53, 0
	v_pk_fma_f32 v[8:9], v[8:9], v[58:59], v[14:15]
	s_waitcnt vmcnt(35)
; __device__ __forceinline__ float bflo(unsigned u) { return __uint_as_float(u << 16); }
; __device__ __forceinline__ float bfhi(unsigned u) { return __uint_as_float(u & 0xffff0000u); }
; __device__ __forceinline__ unsigned pk2(float lo, float hi) { return pg8::cvt_pk_bf16(lo, hi); }
; __device__ __forceinline__ void scan_phase(bf16* U, bf16* So, const float* DEC, int bid, int G, int tid) {
;     ...
;         for (int c0 = 0; c0 < NCH; c0 += SCAN_B) {
;             unsigned ub[SCAN_B]; f32x2 db[SCAN_B];
; #pragma unroll
;             for (int i = 0; i < SCAN_B; ++i) { ub[i] = up[(size_t)(c0 + i) * (NH * HV * HK / 2)]; db[i] = dp[(size_t)(c0 + i) * (DQK / 2)]; }
; #pragma unroll
;             for (int i = 0; i < SCAN_B; ++i) { op[(size_t)(c0 + i) * (NH * HV * HK / 2)] = pk2(s0, s1); s0 = db[i].x * s0 + bflo(ub[i]); s1 = db[i].y * s1 + bfhi(ub[i]); }
	v_cvt_pk_bf16_f32 v12, v8, v9
	global_store_dword v10, v12, s[54:55]
	s_add_u32 s54, s54, 0x40000
	s_addc_u32 s55, s55, 0
	v_lshlrev_b32_e32 v14, 16, v24
	v_and_b32_e32 v15, 0xffff0000, v24
	global_load_dword v24, v10, s[52:53]
	s_add_u32 s52, s52, 0x40000
	s_addc_u32 s53, s53, 0
	v_pk_fma_f32 v[8:9], v[8:9], v[60:61], v[14:15]
	s_waitcnt vmcnt(36)
	v_cvt_pk_bf16_f32 v13, v8, v9
	global_store_dword v10, v13, s[54:55]
	s_add_u32 s54, s54, 0x40000
	s_addc_u32 s55, s55, 0
	v_lshlrev_b32_e32 v14, 16, v25
	v_and_b32_e32 v15, 0xffff0000, v25
	global_load_dword v25, v10, s[52:53]
	s_add_u32 s52, s52, 0x40000
	s_addc_u32 s53, s53, 0
	v_pk_fma_f32 v[8:9], v[8:9], v[62:63], v[14:15]
	s_waitcnt vmcnt(37)
	v_cvt_pk_bf16_f32 v12, v8, v9
	global_store_dword v10, v12, s[54:55]
	s_add_u32 s54, s54, 0x40000
	s_addc_u32 s55, s55, 0
	v_lshlrev_b32_e32 v14, 16, v26
	v_and_b32_e32 v15, 0xffff0000, v26
	global_load_dword v26, v10, s[52:53]
	s_add_u32 s52, s52, 0x40000
	s_addc_u32 s53, s53, 0
	v_pk_fma_f32 v[8:9], v[8:9], v[64:65], v[14:15]
	s_waitcnt vmcnt(38)
	v_cvt_pk_bf16_f32 v13, v8, v9
	global_store_dword v10, v13, s[54:55]
	s_add_u32 s54, s54, 0x40000
	s_addc_u32 s55, s55, 0
	v_lshlrev_b32_e32 v14, 16, v27
	v_and_b32_e32 v15, 0xffff0000, v27
	global_load_dword v27, v10, s[52:53]
	s_add_u32 s52, s52, 0x40000
	s_addc_u32 s53, s53, 0
	v_pk_fma_f32 v[8:9], v[8:9], v[66:67], v[14:15]
	s_waitcnt lgkmcnt(0)
	ds_read_b64 v[52:53], v11 offset:8192
	ds_read_b64 v[54:55], v11 offset:8704
	ds_read_b64 v[56:57], v11 offset:9216
	ds_read_b64 v[58:59], v11 offset:9728
	ds_read_b64 v[60:61], v11 offset:10240
	ds_read_b64 v[62:63], v11 offset:10752
	ds_read_b64 v[64:65], v11 offset:11264
	ds_read_b64 v[66:67], v11 offset:11776
	s_waitcnt vmcnt(39)
	v_cvt_pk_bf16_f32 v12, v8, v9
	global_store_dword v10, v12, s[54:55]
	s_add_u32 s54, s54, 0x40000
	s_addc_u32 s55, s55, 0
	v_lshlrev_b32_e32 v14, 16, v28
	v_and_b32_e32 v15, 0xffff0000, v28
	global_load_dword v28, v10, s[52:53]
	s_add_u32 s52, s52, 0x40000
	s_addc_u32 s53, s53, 0
	v_pk_fma_f32 v[8:9], v[8:9], v[68:69], v[14:15]
	s_waitcnt vmcnt(40)
	v_cvt_pk_bf16_f32 v13, v8, v9
	global_store_dword v10, v13, s[54:55]
	s_add_u32 s54, s54, 0x40000
	s_addc_u32 s55, s55, 0
	v_lshlrev_b32_e32 v14, 16, v29
	v_and_b32_e32 v15, 0xffff0000, v29
	global_load_dword v29, v10, s[52:53]
	s_add_u32 s52, s52, 0x40000
	s_addc_u32 s53, s53, 0
	v_pk_fma_f32 v[8:9], v[8:9], v[70:71], v[14:15]
	s_waitcnt vmcnt(41)
	v_cvt_pk_bf16_f32 v12, v8, v9
	global_store_dword v10, v12, s[54:55]
	s_add_u32 s54, s54, 0x40000
	s_addc_u32 s55, s55, 0
	v_lshlrev_b32_e32 v14, 16, v30
	v_and_b32_e32 v15, 0xffff0000, v30
	global_load_dword v30, v10, s[52:53]
	s_add_u32 s52, s52, 0x40000
	s_addc_u32 s53, s53, 0
	v_pk_fma_f32 v[8:9], v[8:9], v[72:73], v[14:15]
	s_waitcnt vmcnt(42)
	v_cvt_pk_bf16_f32 v13, v8, v9
	global_store_dword v10, v13, s[54:55]
	s_add_u32 s54, s54, 0x40000
	s_addc_u32 s55, s55, 0
	v_lshlrev_b32_e32 v14, 16, v31
	v_and_b32_e32 v15, 0xffff0000, v31
	global_load_dword v31, v10, s[52:53]
	s_add_u32 s52, s52, 0x40000
	s_addc_u32 s53, s53, 0
	v_pk_fma_f32 v[8:9], v[8:9], v[74:75], v[14:15]
	s_waitcnt vmcnt(43)
	v_cvt_pk_bf16_f32 v12, v8, v9
	global_store_dword v10, v12, s[54:55]
	s_add_u32 s54, s54, 0x40000
	s_addc_u32 s55, s55, 0
	v_lshlrev_b32_e32 v14, 16, v32
	v_and_b32_e32 v15, 0xffff0000, v32
	global_load_dword v32, v10, s[52:53]
	s_add_u32 s52, s52, 0x40000
	s_addc_u32 s53, s53, 0
	v_pk_fma_f32 v[8:9], v[8:9], v[76:77], v[14:15]
	s_waitcnt vmcnt(44)
	v_cvt_pk_bf16_f32 v13, v8, v9
	global_store_dword v10, v13, s[54:55]
	s_add_u32 s54, s54, 0x40000
	s_addc_u32 s55, s55, 0
	v_lshlrev_b32_e32 v14, 16, v33
	v_and_b32_e32 v15, 0xffff0000, v33
	global_load_dword v33, v10, s[52:53]
	s_add_u32 s52, s52, 0x40000
	s_addc_u32 s53, s53, 0
	v_pk_fma_f32 v[8:9], v[8:9], v[78:79], v[14:15]
	s_waitcnt vmcnt(45)
	v_cvt_pk_bf16_f32 v12, v8, v9
	global_store_dword v10, v12, s[54:55]
	s_add_u32 s54, s54, 0x40000
	s_addc_u32 s55, s55, 0
	v_lshlrev_b32_e32 v14, 16, v34
	v_and_b32_e32 v15, 0xffff0000, v34
	global_load_dword v34, v10, s[52:53]
	s_add_u32 s52, s52, 0x40000
	s_addc_u32 s53, s53, 0
	v_pk_fma_f32 v[8:9], v[8:9], v[80:81], v[14:15]
	s_waitcnt vmcnt(46)
	v_cvt_pk_bf16_f32 v13, v8, v9
	global_store_dword v10, v13, s[54:55]
	s_add_u32 s54, s54, 0x40000
	s_addc_u32 s55, s55, 0
	v_lshlrev_b32_e32 v14, 16, v35
	v_and_b32_e32 v15, 0xffff0000, v35
	global_load_dword v35, v10, s[52:53]
	s_add_u32 s52, s52, 0x40000
	s_addc_u32 s53, s53, 0
	v_pk_fma_f32 v[8:9], v[8:9], v[82:83], v[14:15]
	s_waitcnt lgkmcnt(0)
	ds_read_b64 v[68:69], v11 offset:12288
	ds_read_b64 v[70:71], v11 offset:12800
	ds_read_b64 v[72:73], v11 offset:13312
	ds_read_b64 v[74:75], v11 offset:13824
	ds_read_b64 v[76:77], v11 offset:14336
	ds_read_b64 v[78:79], v11 offset:14848
	ds_read_b64 v[80:81], v11 offset:15360
	ds_read_b64 v[82:83], v11 offset:15872
	s_waitcnt vmcnt(47)
	v_cvt_pk_bf16_f32 v12, v8, v9
	global_store_dword v10, v12, s[54:55]
	s_add_u32 s54, s54, 0x40000
	s_addc_u32 s55, s55, 0
	v_lshlrev_b32_e32 v14, 16, v36
	v_and_b32_e32 v15, 0xffff0000, v36
	global_load_dword v36, v10, s[52:53]
	s_add_u32 s52, s52, 0x40000
	s_addc_u32 s53, s53, 0
	v_pk_fma_f32 v[8:9], v[8:9], v[52:53], v[14:15]
	s_waitcnt vmcnt(48)
	v_cvt_pk_bf16_f32 v13, v8, v9
	global_store_dword v10, v13, s[54:55]
	s_add_u32 s54, s54, 0x40000
	s_addc_u32 s55, s55, 0
	v_lshlrev_b32_e32 v14, 16, v37
	v_and_b32_e32 v15, 0xffff0000, v37
	global_load_dword v37, v10, s[52:53]
	s_add_u32 s52, s52, 0x40000
	s_addc_u32 s53, s53, 0
	v_pk_fma_f32 v[8:9], v[8:9], v[54:55], v[14:15]
	s_waitcnt vmcnt(49)
; __device__ __forceinline__ float bflo(unsigned u) { return __uint_as_float(u << 16); }
; __device__ __forceinline__ float bfhi(unsigned u) { return __uint_as_float(u & 0xffff0000u); }
; __device__ __forceinline__ unsigned pk2(float lo, float hi) { return pg8::cvt_pk_bf16(lo, hi); }
; __device__ __forceinline__ void scan_phase(bf16* U, bf16* So, const float* DEC, int bid, int G, int tid) {
;     ...
;         for (int c0 = 0; c0 < NCH; c0 += SCAN_B) {
;             unsigned ub[SCAN_B]; f32x2 db[SCAN_B];
; #pragma unroll
;             for (int i = 0; i < SCAN_B; ++i) { ub[i] = up[(size_t)(c0 + i) * (NH * HV * HK / 2)]; db[i] = dp[(size_t)(c0 + i) * (DQK / 2)]; }
; #pragma unroll
;             for (int i = 0; i < SCAN_B; ++i) { op[(size_t)(c0 + i) * (NH * HV * HK / 2)] = pk2(s0, s1); s0 = db[i].x * s0 + bflo(ub[i]); s1 = db[i].y * s1 + bfhi(ub[i]); }
	v_cvt_pk_bf16_f32 v12, v8, v9
	global_store_dword v10, v12, s[54:55]
	s_add_u32 s54, s54, 0x40000
	s_addc_u32 s55, s55, 0
	v_lshlrev_b32_e32 v14, 16, v38
	v_and_b32_e32 v15, 0xffff0000, v38
	global_load_dword v38, v10, s[52:53]
	s_add_u32 s52, s52, 0x40000
	s_addc_u32 s53, s53, 0
	v_pk_fma_f32 v[8:9], v[8:9], v[56:57], v[14:15]
	s_waitcnt vmcnt(50)
	v_cvt_pk_bf16_f32 v13, v8, v9
	global_store_dword v10, v13, s[54:55]
	s_add_u32 s54, s54, 0x40000
	s_addc_u32 s55, s55, 0
	v_lshlrev_b32_e32 v14, 16, v39
	v_and_b32_e32 v15, 0xffff0000, v39
	global_load_dword v39, v10, s[52:53]
	s_add_u32 s52, s52, 0x40000
	s_addc_u32 s53, s53, 0
	v_pk_fma_f32 v[8:9], v[8:9], v[58:59], v[14:15]
	s_waitcnt vmcnt(51)
	v_cvt_pk_bf16_f32 v12, v8, v9
	global_store_dword v10, v12, s[54:55]
	s_add_u32 s54, s54, 0x40000
	s_addc_u32 s55, s55, 0
	v_lshlrev_b32_e32 v14, 16, v40
	v_and_b32_e32 v15, 0xffff0000, v40
	global_load_dword v40, v10, s[52:53]
	s_add_u32 s52, s52, 0x40000
	s_addc_u32 s53, s53, 0
	v_pk_fma_f32 v[8:9], v[8:9], v[60:61], v[14:15]
	s_waitcnt vmcnt(52)
	v_cvt_pk_bf16_f32 v13, v8, v9
	global_store_dword v10, v13, s[54:55]
	s_add_u32 s54, s54, 0x40000
	s_addc_u32 s55, s55, 0
	v_lshlrev_b32_e32 v14, 16, v41
	v_and_b32_e32 v15, 0xffff0000, v41
	global_load_dword v41, v10, s[52:53]
	s_add_u32 s52, s52, 0x40000
	s_addc_u32 s53, s53, 0
	v_pk_fma_f32 v[8:9], v[8:9], v[62:63], v[14:15]
	s_waitcnt vmcnt(53)
	v_cvt_pk_bf16_f32 v12, v8, v9
	global_store_dword v10, v12, s[54:55]
	s_add_u32 s54, s54, 0x40000
	s_addc_u32 s55, s55, 0
	v_lshlrev_b32_e32 v14, 16, v42
	v_and_b32_e32 v15, 0xffff0000, v42
	global_load_dword v42, v10, s[52:53]
	s_add_u32 s52, s52, 0x40000
	s_addc_u32 s53, s53, 0
	v_pk_fma_f32 v[8:9], v[8:9], v[64:65], v[14:15]
	s_waitcnt vmcnt(54)
	v_cvt_pk_bf16_f32 v13, v8, v9
	global_store_dword v10, v13, s[54:55]
	s_add_u32 s54, s54, 0x40000
	s_addc_u32 s55, s55, 0
	v_lshlrev_b32_e32 v14, 16, v43
	v_and_b32_e32 v15, 0xffff0000, v43
	global_load_dword v43, v10, s[52:53]
	s_add_u32 s52, s52, 0x40000
	s_addc_u32 s53, s53, 0
	v_pk_fma_f32 v[8:9], v[8:9], v[66:67], v[14:15]
	s_waitcnt lgkmcnt(0)
	ds_read_b64 v[52:53], v11 offset:16384
	ds_read_b64 v[54:55], v11 offset:16896
	ds_read_b64 v[56:57], v11 offset:17408
	ds_read_b64 v[58:59], v11 offset:17920
	ds_read_b64 v[60:61], v11 offset:18432
	ds_read_b64 v[62:63], v11 offset:18944
	ds_read_b64 v[64:65], v11 offset:19456
	ds_read_b64 v[66:67], v11 offset:19968
	s_waitcnt vmcnt(55)
	v_cvt_pk_bf16_f32 v12, v8, v9
	global_store_dword v10, v12, s[54:55]
	s_add_u32 s54, s54, 0x40000
	s_addc_u32 s55, s55, 0
	v_lshlrev_b32_e32 v14, 16, v44
	v_and_b32_e32 v15, 0xffff0000, v44
	global_load_dword v44, v10, s[52:53]
	s_add_u32 s52, s52, 0x40000
	s_addc_u32 s53, s53, 0
	v_pk_fma_f32 v[8:9], v[8:9], v[68:69], v[14:15]
	s_waitcnt vmcnt(56)
	v_cvt_pk_bf16_f32 v13, v8, v9
	global_store_dword v10, v13, s[54:55]
	s_add_u32 s54, s54, 0x40000
	s_addc_u32 s55, s55, 0
	v_lshlrev_b32_e32 v14, 16, v45
	v_and_b32_e32 v15, 0xffff0000, v45
	global_load_dword v45, v10, s[52:53]
	s_add_u32 s52, s52, 0x40000
	s_addc_u32 s53, s53, 0
	v_pk_fma_f32 v[8:9], v[8:9], v[70:71], v[14:15]
	s_waitcnt vmcnt(57)
	v_cvt_pk_bf16_f32 v12, v8, v9
	global_store_dword v10, v12, s[54:55]
	s_add_u32 s54, s54, 0x40000
	s_addc_u32 s55, s55, 0
	v_lshlrev_b32_e32 v14, 16, v46
	v_and_b32_e32 v15, 0xffff0000, v46
	global_load_dword v46, v10, s[52:53]
	s_add_u32 s52, s52, 0x40000
	s_addc_u32 s53, s53, 0
	v_pk_fma_f32 v[8:9], v[8:9], v[72:73], v[14:15]
	s_waitcnt vmcnt(58)
	v_cvt_pk_bf16_f32 v13, v8, v9
	global_store_dword v10, v13, s[54:55]
	s_add_u32 s54, s54, 0x40000
	s_addc_u32 s55, s55, 0
	v_lshlrev_b32_e32 v14, 16, v47
	v_and_b32_e32 v15, 0xffff0000, v47
	global_load_dword v47, v10, s[52:53]
	s_add_u32 s52, s52, 0x40000
	s_addc_u32 s53, s53, 0
	v_pk_fma_f32 v[8:9], v[8:9], v[74:75], v[14:15]
	s_waitcnt vmcnt(59)
	v_cvt_pk_bf16_f32 v12, v8, v9
	global_store_dword v10, v12, s[54:55]
	s_add_u32 s54, s54, 0x40000
	s_addc_u32 s55, s55, 0
	v_lshlrev_b32_e32 v14, 16, v48
	v_and_b32_e32 v15, 0xffff0000, v48
	global_load_dword v48, v10, s[52:53]
	s_add_u32 s52, s52, 0x40000
	s_addc_u32 s53, s53, 0
	v_pk_fma_f32 v[8:9], v[8:9], v[76:77], v[14:15]
	s_waitcnt vmcnt(60)
	v_cvt_pk_bf16_f32 v13, v8, v9
	global_store_dword v10, v13, s[54:55]
	s_add_u32 s54, s54, 0x40000
	s_addc_u32 s55, s55, 0
	v_lshlrev_b32_e32 v14, 16, v49
	v_and_b32_e32 v15, 0xffff0000, v49
	global_load_dword v49, v10, s[52:53]
	s_add_u32 s52, s52, 0x40000
	s_addc_u32 s53, s53, 0
	v_pk_fma_f32 v[8:9], v[8:9], v[78:79], v[14:15]
	s_waitcnt vmcnt(61)
	v_cvt_pk_bf16_f32 v12, v8, v9
	global_store_dword v10, v12, s[54:55]
	s_add_u32 s54, s54, 0x40000
	s_addc_u32 s55, s55, 0
	v_lshlrev_b32_e32 v14, 16, v50
	v_and_b32_e32 v15, 0xffff0000, v50
	global_load_dword v50, v10, s[52:53]
	s_add_u32 s52, s52, 0x40000
	s_addc_u32 s53, s53, 0
	v_pk_fma_f32 v[8:9], v[8:9], v[80:81], v[14:15]
	s_waitcnt vmcnt(62)
	v_cvt_pk_bf16_f32 v13, v8, v9
	global_store_dword v10, v13, s[54:55]
	s_add_u32 s54, s54, 0x40000
	s_addc_u32 s55, s55, 0
	v_lshlrev_b32_e32 v14, 16, v51
	v_and_b32_e32 v15, 0xffff0000, v51
	global_load_dword v51, v10, s[52:53]
	s_add_u32 s52, s52, 0x40000
	s_addc_u32 s53, s53, 0
	v_pk_fma_f32 v[8:9], v[8:9], v[82:83], v[14:15]
	v_add_u32_e32 v11, 0x4000, v11
	s_movk_i32 s27, 7
; __device__ __forceinline__ float bflo(unsigned u) { return __uint_as_float(u << 16); }
; __device__ __forceinline__ float bfhi(unsigned u) { return __uint_as_float(u & 0xffff0000u); }
; __device__ __forceinline__ unsigned pk2(float lo, float hi) { return pg8::cvt_pk_bf16(lo, hi); }
; __device__ __forceinline__ void scan_phase(bf16* U, bf16* So, const float* DEC, int bid, int G, int tid) {
;     ...
;         for (int c0 = 0; c0 < NCH; c0 += SCAN_B) {
;             unsigned ub[SCAN_B]; f32x2 db[SCAN_B];
; #pragma unroll
;             for (int i = 0; i < SCAN_B; ++i) { ub[i] = up[(size_t)(c0 + i) * (NH * HV * HK / 2)]; db[i] = dp[(size_t)(c0 + i) * (DQK / 2)]; }
; #pragma unroll
;             for (int i = 0; i < SCAN_B; ++i) { op[(size_t)(c0 + i) * (NH * HV * HK / 2)] = pk2(s0, s1); s0 = db[i].x * s0 + bflo(ub[i]); s1 = db[i].y * s1 + bfhi(ub[i]); }
.Lscan_loop:
	s_waitcnt lgkmcnt(0)
	ds_read_b64 v[68:69], v11 offset:4096
	ds_read_b64 v[70:71], v11 offset:4608
	ds_read_b64 v[72:73], v11 offset:5120
	ds_read_b64 v[74:75], v11 offset:5632
	ds_read_b64 v[76:77], v11 offset:6144
	ds_read_b64 v[78:79], v11 offset:6656
	ds_read_b64 v[80:81], v11 offset:7168
	ds_read_b64 v[82:83], v11 offset:7680
	s_waitcnt vmcnt(62)
	v_cvt_pk_bf16_f32 v12, v8, v9
	global_store_dword v10, v12, s[54:55]
	s_add_u32 s54, s54, 0x40000
	s_addc_u32 s55, s55, 0
	v_lshlrev_b32_e32 v14, 16, v20
	v_and_b32_e32 v15, 0xffff0000, v20
	global_load_dword v20, v10, s[52:53]
	s_add_u32 s52, s52, 0x40000
	s_addc_u32 s53, s53, 0
	v_pk_fma_f32 v[8:9], v[8:9], v[52:53], v[14:15]
	s_waitcnt vmcnt(62)
	v_cvt_pk_bf16_f32 v13, v8, v9
	global_store_dword v10, v13, s[54:55]
	s_add_u32 s54, s54, 0x40000
	s_addc_u32 s55, s55, 0
	v_lshlrev_b32_e32 v14, 16, v21
	v_and_b32_e32 v15, 0xffff0000, v21
	global_load_dword v21, v10, s[52:53]
	s_add_u32 s52, s52, 0x40000
	s_addc_u32 s53, s53, 0
	v_pk_fma_f32 v[8:9], v[8:9], v[54:55], v[14:15]
	s_waitcnt vmcnt(62)
	v_cvt_pk_bf16_f32 v12, v8, v9
	global_store_dword v10, v12, s[54:55]
	s_add_u32 s54, s54, 0x40000
	s_addc_u32 s55, s55, 0
	v_lshlrev_b32_e32 v14, 16, v22
	v_and_b32_e32 v15, 0xffff0000, v22
	global_load_dword v22, v10, s[52:53]
	s_add_u32 s52, s52, 0x40000
	s_addc_u32 s53, s53, 0
	v_pk_fma_f32 v[8:9], v[8:9], v[56:57], v[14:15]
	s_waitcnt vmcnt(62)
	v_cvt_pk_bf16_f32 v13, v8, v9
	global_store_dword v10, v13, s[54:55]
	s_add_u32 s54, s54, 0x40000
	s_addc_u32 s55, s55, 0
	v_lshlrev_b32_e32 v14, 16, v23
	v_and_b32_e32 v15, 0xffff0000, v23
	global_load_dword v23, v10, s[52:53]
	s_add_u32 s52, s52, 0x40000
	s_addc_u32 s53, s53, 0
	v_pk_fma_f32 v[8:9], v[8:9], v[58:59], v[14:15]
	s_waitcnt vmcnt(62)
	v_cvt_pk_bf16_f32 v12, v8, v9
	global_store_dword v10, v12, s[54:55]
	s_add_u32 s54, s54, 0x40000
	s_addc_u32 s55, s55, 0
	v_lshlrev_b32_e32 v14, 16, v24
	v_and_b32_e32 v15, 0xffff0000, v24
	global_load_dword v24, v10, s[52:53]
	s_add_u32 s52, s52, 0x40000
	s_addc_u32 s53, s53, 0
	v_pk_fma_f32 v[8:9], v[8:9], v[60:61], v[14:15]
	s_waitcnt vmcnt(62)
	v_cvt_pk_bf16_f32 v13, v8, v9
	global_store_dword v10, v13, s[54:55]
	s_add_u32 s54, s54, 0x40000
	s_addc_u32 s55, s55, 0
	v_lshlrev_b32_e32 v14, 16, v25
	v_and_b32_e32 v15, 0xffff0000, v25
	global_load_dword v25, v10, s[52:53]
	s_add_u32 s52, s52, 0x40000
	s_addc_u32 s53, s53, 0
	v_pk_fma_f32 v[8:9], v[8:9], v[62:63], v[14:15]
	s_waitcnt vmcnt(62)
	v_cvt_pk_bf16_f32 v12, v8, v9
	global_store_dword v10, v12, s[54:55]
	s_add_u32 s54, s54, 0x40000
	s_addc_u32 s55, s55, 0
	v_lshlrev_b32_e32 v14, 16, v26
	v_and_b32_e32 v15, 0xffff0000, v26
	global_load_dword v26, v10, s[52:53]
	s_add_u32 s52, s52, 0x40000
	s_addc_u32 s53, s53, 0
	v_pk_fma_f32 v[8:9], v[8:9], v[64:65], v[14:15]
	s_waitcnt vmcnt(62)
	v_cvt_pk_bf16_f32 v13, v8, v9
	global_store_dword v10, v13, s[54:55]
	s_add_u32 s54, s54, 0x40000
	s_addc_u32 s55, s55, 0
	v_lshlrev_b32_e32 v14, 16, v27
	v_and_b32_e32 v15, 0xffff0000, v27
	global_load_dword v27, v10, s[52:53]
	s_add_u32 s52, s52, 0x40000
	s_addc_u32 s53, s53, 0
	v_pk_fma_f32 v[8:9], v[8:9], v[66:67], v[14:15]
	s_waitcnt lgkmcnt(0)
	ds_read_b64 v[52:53], v11 offset:8192
	ds_read_b64 v[54:55], v11 offset:8704
	ds_read_b64 v[56:57], v11 offset:9216
	ds_read_b64 v[58:59], v11 offset:9728
	ds_read_b64 v[60:61], v11 offset:10240
	ds_read_b64 v[62:63], v11 offset:10752
	ds_read_b64 v[64:65], v11 offset:11264
	ds_read_b64 v[66:67], v11 offset:11776
	s_waitcnt vmcnt(62)
	v_cvt_pk_bf16_f32 v12, v8, v9
	global_store_dword v10, v12, s[54:55]
	s_add_u32 s54, s54, 0x40000
	s_addc_u32 s55, s55, 0
	v_lshlrev_b32_e32 v14, 16, v28
	v_and_b32_e32 v15, 0xffff0000, v28
	global_load_dword v28, v10, s[52:53]
	s_add_u32 s52, s52, 0x40000
	s_addc_u32 s53, s53, 0
	v_pk_fma_f32 v[8:9], v[8:9], v[68:69], v[14:15]
	s_waitcnt vmcnt(62)
	v_cvt_pk_bf16_f32 v13, v8, v9
	global_store_dword v10, v13, s[54:55]
	s_add_u32 s54, s54, 0x40000
	s_addc_u32 s55, s55, 0
	v_lshlrev_b32_e32 v14, 16, v29
	v_and_b32_e32 v15, 0xffff0000, v29
	global_load_dword v29, v10, s[52:53]
	s_add_u32 s52, s52, 0x40000
	s_addc_u32 s53, s53, 0
	v_pk_fma_f32 v[8:9], v[8:9], v[70:71], v[14:15]
	s_waitcnt vmcnt(62)
	v_cvt_pk_bf16_f32 v12, v8, v9
	global_store_dword v10, v12, s[54:55]
	s_add_u32 s54, s54, 0x40000
	s_addc_u32 s55, s55, 0
	v_lshlrev_b32_e32 v14, 16, v30
	v_and_b32_e32 v15, 0xffff0000, v30
	global_load_dword v30, v10, s[52:53]
	s_add_u32 s52, s52, 0x40000
	s_addc_u32 s53, s53, 0
	v_pk_fma_f32 v[8:9], v[8:9], v[72:73], v[14:15]
	s_waitcnt vmcnt(62)
	v_cvt_pk_bf16_f32 v13, v8, v9
	global_store_dword v10, v13, s[54:55]
	s_add_u32 s54, s54, 0x40000
	s_addc_u32 s55, s55, 0
	v_lshlrev_b32_e32 v14, 16, v31
	v_and_b32_e32 v15, 0xffff0000, v31
	global_load_dword v31, v10, s[52:53]
	s_add_u32 s52, s52, 0x40000
	s_addc_u32 s53, s53, 0
	v_pk_fma_f32 v[8:9], v[8:9], v[74:75], v[14:15]
	s_waitcnt vmcnt(62)
	v_cvt_pk_bf16_f32 v12, v8, v9
	global_store_dword v10, v12, s[54:55]
	s_add_u32 s54, s54, 0x40000
	s_addc_u32 s55, s55, 0
	v_lshlrev_b32_e32 v14, 16, v32
	v_and_b32_e32 v15, 0xffff0000, v32
	global_load_dword v32, v10, s[52:53]
	s_add_u32 s52, s52, 0x40000
	s_addc_u32 s53, s53, 0
	v_pk_fma_f32 v[8:9], v[8:9], v[76:77], v[14:15]
	s_waitcnt vmcnt(62)
	v_cvt_pk_bf16_f32 v13, v8, v9
	global_store_dword v10, v13, s[54:55]
	s_add_u32 s54, s54, 0x40000
	s_addc_u32 s55, s55, 0
	v_lshlrev_b32_e32 v14, 16, v33
	v_and_b32_e32 v15, 0xffff0000, v33
	global_load_dword v33, v10, s[52:53]
	s_add_u32 s52, s52, 0x40000
	s_addc_u32 s53, s53, 0
	v_pk_fma_f32 v[8:9], v[8:9], v[78:79], v[14:15]
	s_waitcnt vmcnt(62)
; __device__ __forceinline__ float bflo(unsigned u) { return __uint_as_float(u << 16); }
; __device__ __forceinline__ float bfhi(unsigned u) { return __uint_as_float(u & 0xffff0000u); }
; __device__ __forceinline__ unsigned pk2(float lo, float hi) { return pg8::cvt_pk_bf16(lo, hi); }
; __device__ __forceinline__ void scan_phase(bf16* U, bf16* So, const float* DEC, int bid, int G, int tid) {
;     ...
;         for (int c0 = 0; c0 < NCH; c0 += SCAN_B) {
;             unsigned ub[SCAN_B]; f32x2 db[SCAN_B];
; #pragma unroll
;             for (int i = 0; i < SCAN_B; ++i) { ub[i] = up[(size_t)(c0 + i) * (NH * HV * HK / 2)]; db[i] = dp[(size_t)(c0 + i) * (DQK / 2)]; }
; #pragma unroll
;             for (int i = 0; i < SCAN_B; ++i) { op[(size_t)(c0 + i) * (NH * HV * HK / 2)] = pk2(s0, s1); s0 = db[i].x * s0 + bflo(ub[i]); s1 = db[i].y * s1 + bfhi(ub[i]); }
	v_cvt_pk_bf16_f32 v12, v8, v9
	global_store_dword v10, v12, s[54:55]
	s_add_u32 s54, s54, 0x40000
	s_addc_u32 s55, s55, 0
	v_lshlrev_b32_e32 v14, 16, v34
	v_and_b32_e32 v15, 0xffff0000, v34
	global_load_dword v34, v10, s[52:53]
	s_add_u32 s52, s52, 0x40000
	s_addc_u32 s53, s53, 0
	v_pk_fma_f32 v[8:9], v[8:9], v[80:81], v[14:15]
	s_waitcnt vmcnt(62)
	v_cvt_pk_bf16_f32 v13, v8, v9
	global_store_dword v10, v13, s[54:55]
	s_add_u32 s54, s54, 0x40000
	s_addc_u32 s55, s55, 0
	v_lshlrev_b32_e32 v14, 16, v35
	v_and_b32_e32 v15, 0xffff0000, v35
	global_load_dword v35, v10, s[52:53]
	s_add_u32 s52, s52, 0x40000
	s_addc_u32 s53, s53, 0
	v_pk_fma_f32 v[8:9], v[8:9], v[82:83], v[14:15]
	s_waitcnt lgkmcnt(0)
	ds_read_b64 v[68:69], v11 offset:12288
	ds_read_b64 v[70:71], v11 offset:12800
	ds_read_b64 v[72:73], v11 offset:13312
	ds_read_b64 v[74:75], v11 offset:13824
	ds_read_b64 v[76:77], v11 offset:14336
	ds_read_b64 v[78:79], v11 offset:14848
	ds_read_b64 v[80:81], v11 offset:15360
	ds_read_b64 v[82:83], v11 offset:15872
	s_waitcnt vmcnt(62)
	v_cvt_pk_bf16_f32 v12, v8, v9
	global_store_dword v10, v12, s[54:55]
	s_add_u32 s54, s54, 0x40000
	s_addc_u32 s55, s55, 0
	v_lshlrev_b32_e32 v14, 16, v36
	v_and_b32_e32 v15, 0xffff0000, v36
	global_load_dword v36, v10, s[52:53]
	s_add_u32 s52, s52, 0x40000
	s_addc_u32 s53, s53, 0
	v_pk_fma_f32 v[8:9], v[8:9], v[52:53], v[14:15]
	s_waitcnt vmcnt(62)
	v_cvt_pk_bf16_f32 v13, v8, v9
	global_store_dword v10, v13, s[54:55]
	s_add_u32 s54, s54, 0x40000
	s_addc_u32 s55, s55, 0
	v_lshlrev_b32_e32 v14, 16, v37
	v_and_b32_e32 v15, 0xffff0000, v37
	global_load_dword v37, v10, s[52:53]
	s_add_u32 s52, s52, 0x40000
	s_addc_u32 s53, s53, 0
	v_pk_fma_f32 v[8:9], v[8:9], v[54:55], v[14:15]
	s_waitcnt vmcnt(62)
	v_cvt_pk_bf16_f32 v12, v8, v9
	global_store_dword v10, v12, s[54:55]
	s_add_u32 s54, s54, 0x40000
	s_addc_u32 s55, s55, 0
	v_lshlrev_b32_e32 v14, 16, v38
	v_and_b32_e32 v15, 0xffff0000, v38
	global_load_dword v38, v10, s[52:53]
	s_add_u32 s52, s52, 0x40000
	s_addc_u32 s53, s53, 0
	v_pk_fma_f32 v[8:9], v[8:9], v[56:57], v[14:15]
	s_waitcnt vmcnt(62)
	v_cvt_pk_bf16_f32 v13, v8, v9
	global_store_dword v10, v13, s[54:55]
	s_add_u32 s54, s54, 0x40000
	s_addc_u32 s55, s55, 0
	v_lshlrev_b32_e32 v14, 16, v39
	v_and_b32_e32 v15, 0xffff0000, v39
	global_load_dword v39, v10, s[52:53]
	s_add_u32 s52, s52, 0x40000
	s_addc_u32 s53, s53, 0
	v_pk_fma_f32 v[8:9], v[8:9], v[58:59], v[14:15]
	s_waitcnt vmcnt(62)
	v_cvt_pk_bf16_f32 v12, v8, v9
	global_store_dword v10, v12, s[54:55]
	s_add_u32 s54, s54, 0x40000
	s_addc_u32 s55, s55, 0
	v_lshlrev_b32_e32 v14, 16, v40
	v_and_b32_e32 v15, 0xffff0000, v40
	global_load_dword v40, v10, s[52:53]
	s_add_u32 s52, s52, 0x40000
	s_addc_u32 s53, s53, 0
	v_pk_fma_f32 v[8:9], v[8:9], v[60:61], v[14:15]
	s_waitcnt vmcnt(62)
	v_cvt_pk_bf16_f32 v13, v8, v9
	global_store_dword v10, v13, s[54:55]
	s_add_u32 s54, s54, 0x40000
	s_addc_u32 s55, s55, 0
	v_lshlrev_b32_e32 v14, 16, v41
	v_and_b32_e32 v15, 0xffff0000, v41
	global_load_dword v41, v10, s[52:53]
	s_add_u32 s52, s52, 0x40000
	s_addc_u32 s53, s53, 0
	v_pk_fma_f32 v[8:9], v[8:9], v[62:63], v[14:15]
	s_waitcnt vmcnt(62)
	v_cvt_pk_bf16_f32 v12, v8, v9
	global_store_dword v10, v12, s[54:55]
	s_add_u32 s54, s54, 0x40000
	s_addc_u32 s55, s55, 0
	v_lshlrev_b32_e32 v14, 16, v42
	v_and_b32_e32 v15, 0xffff0000, v42
	global_load_dword v42, v10, s[52:53]
	s_add_u32 s52, s52, 0x40000
	s_addc_u32 s53, s53, 0
	v_pk_fma_f32 v[8:9], v[8:9], v[64:65], v[14:15]
	s_waitcnt vmcnt(62)
; __device__ __forceinline__ float bflo(unsigned u) { return __uint_as_float(u << 16); }
; __device__ __forceinline__ float bfhi(unsigned u) { return __uint_as_float(u & 0xffff0000u); }
; __device__ __forceinline__ unsigned pk2(float lo, float hi) { return pg8::cvt_pk_bf16(lo, hi); }
; __device__ __forceinline__ void scan_phase(bf16* U, bf16* So, const float* DEC, int bid, int G, int tid) {
;     ...
;     for (int e = bid * 256 + tid; e < NH * HV * (HK / 2); e += G * 256) {
;         const int hd = e >> 14, rem = e & 16383, v = rem >> 6, kp = rem & 63;
;         unsigned* up = (unsigned*)(U + ((size_t)hd * HV + v) * HK + 2 * kp);
;         unsigned* op = (unsigned*)(So + ((size_t)hd * HV + v) * HK + 2 * kp);
;         const f32x2* dp = (const f32x2*)(DEC + hd * HK + 2 * kp);
;     ...
;         for (int c0 = 0; c0 < NCH; c0 += SCAN_B) {
;             unsigned ub[SCAN_B]; f32x2 db[SCAN_B];
; #pragma unroll
;             for (int i = 0; i < SCAN_B; ++i) { ub[i] = up[(size_t)(c0 + i) * (NH * HV * HK / 2)]; db[i] = dp[(size_t)(c0 + i) * (DQK / 2)]; }
; #pragma unroll
;             for (int i = 0; i < SCAN_B; ++i) { op[(size_t)(c0 + i) * (NH * HV * HK / 2)] = pk2(s0, s1); s0 = db[i].x * s0 + bflo(ub[i]); s1 = db[i].y * s1 + bfhi(ub[i]); }
	v_cvt_pk_bf16_f32 v13, v8, v9
	global_store_dword v10, v13, s[54:55]
	s_add_u32 s54, s54, 0x40000
	s_addc_u32 s55, s55, 0
	v_lshlrev_b32_e32 v14, 16, v43
	v_and_b32_e32 v15, 0xffff0000, v43
	global_load_dword v43, v10, s[52:53]
	s_add_u32 s52, s52, 0x40000
	s_addc_u32 s53, s53, 0
	v_pk_fma_f32 v[8:9], v[8:9], v[66:67], v[14:15]
	s_waitcnt lgkmcnt(0)
	ds_read_b64 v[52:53], v11 offset:16384
	ds_read_b64 v[54:55], v11 offset:16896
	ds_read_b64 v[56:57], v11 offset:17408
	ds_read_b64 v[58:59], v11 offset:17920
	ds_read_b64 v[60:61], v11 offset:18432
	ds_read_b64 v[62:63], v11 offset:18944
	ds_read_b64 v[64:65], v11 offset:19456
	ds_read_b64 v[66:67], v11 offset:19968
	s_waitcnt vmcnt(62)
	v_cvt_pk_bf16_f32 v12, v8, v9
	global_store_dword v10, v12, s[54:55]
	s_add_u32 s54, s54, 0x40000
	s_addc_u32 s55, s55, 0
	v_lshlrev_b32_e32 v14, 16, v44
	v_and_b32_e32 v15, 0xffff0000, v44
	global_load_dword v44, v10, s[52:53]
	s_add_u32 s52, s52, 0x40000
	s_addc_u32 s53, s53, 0
	v_pk_fma_f32 v[8:9], v[8:9], v[68:69], v[14:15]
	s_waitcnt vmcnt(62)
	v_cvt_pk_bf16_f32 v13, v8, v9
	global_store_dword v10, v13, s[54:55]
	s_add_u32 s54, s54, 0x40000
	s_addc_u32 s55, s55, 0
	v_lshlrev_b32_e32 v14, 16, v45
	v_and_b32_e32 v15, 0xffff0000, v45
	global_load_dword v45, v10, s[52:53]
	s_add_u32 s52, s52, 0x40000
	s_addc_u32 s53, s53, 0
	v_pk_fma_f32 v[8:9], v[8:9], v[70:71], v[14:15]
	s_waitcnt vmcnt(62)
	v_cvt_pk_bf16_f32 v12, v8, v9
	global_store_dword v10, v12, s[54:55]
	s_add_u32 s54, s54, 0x40000
	s_addc_u32 s55, s55, 0
	v_lshlrev_b32_e32 v14, 16, v46
	v_and_b32_e32 v15, 0xffff0000, v46
	global_load_dword v46, v10, s[52:53]
	s_add_u32 s52, s52, 0x40000
	s_addc_u32 s53, s53, 0
	v_pk_fma_f32 v[8:9], v[8:9], v[72:73], v[14:15]
	s_waitcnt vmcnt(62)
	v_cvt_pk_bf16_f32 v13, v8, v9
	global_store_dword v10, v13, s[54:55]
	s_add_u32 s54, s54, 0x40000
	s_addc_u32 s55, s55, 0
	v_lshlrev_b32_e32 v14, 16, v47
	v_and_b32_e32 v15, 0xffff0000, v47
	global_load_dword v47, v10, s[52:53]
	s_add_u32 s52, s52, 0x40000
	s_addc_u32 s53, s53, 0
	v_pk_fma_f32 v[8:9], v[8:9], v[74:75], v[14:15]
	s_waitcnt vmcnt(62)
	v_cvt_pk_bf16_f32 v12, v8, v9
	global_store_dword v10, v12, s[54:55]
	s_add_u32 s54, s54, 0x40000
	s_addc_u32 s55, s55, 0
	v_lshlrev_b32_e32 v14, 16, v48
	v_and_b32_e32 v15, 0xffff0000, v48
	global_load_dword v48, v10, s[52:53]
	s_add_u32 s52, s52, 0x40000
	s_addc_u32 s53, s53, 0
	v_pk_fma_f32 v[8:9], v[8:9], v[76:77], v[14:15]
	s_waitcnt vmcnt(62)
	v_cvt_pk_bf16_f32 v13, v8, v9
	global_store_dword v10, v13, s[54:55]
	s_add_u32 s54, s54, 0x40000
	s_addc_u32 s55, s55, 0
	v_lshlrev_b32_e32 v14, 16, v49
	v_and_b32_e32 v15, 0xffff0000, v49
	global_load_dword v49, v10, s[52:53]
	s_add_u32 s52, s52, 0x40000
	s_addc_u32 s53, s53, 0
	v_pk_fma_f32 v[8:9], v[8:9], v[78:79], v[14:15]
	s_waitcnt vmcnt(62)
	v_cvt_pk_bf16_f32 v12, v8, v9
	global_store_dword v10, v12, s[54:55]
	s_add_u32 s54, s54, 0x40000
	s_addc_u32 s55, s55, 0
	v_lshlrev_b32_e32 v14, 16, v50
	v_and_b32_e32 v15, 0xffff0000, v50
	global_load_dword v50, v10, s[52:53]
	s_add_u32 s52, s52, 0x40000
	s_addc_u32 s53, s53, 0
	v_pk_fma_f32 v[8:9], v[8:9], v[80:81], v[14:15]
	s_waitcnt vmcnt(62)
	v_cvt_pk_bf16_f32 v13, v8, v9
	global_store_dword v10, v13, s[54:55]
	s_add_u32 s54, s54, 0x40000
	s_addc_u32 s55, s55, 0
	v_lshlrev_b32_e32 v14, 16, v51
	v_and_b32_e32 v15, 0xffff0000, v51
	global_load_dword v51, v10, s[52:53]
	s_add_u32 s52, s52, 0x40000
	s_addc_u32 s53, s53, 0
	v_pk_fma_f32 v[8:9], v[8:9], v[82:83], v[14:15]
	v_add_u32_e32 v11, 0x4000, v11
	s_sub_u32 s27, s27, 1
	s_cmp_lg_u32 s27, 0
	s_cbranch_scc1 .Lscan_loop
	s_branch .LBB0_495
.Lscan_orig:
	v_readlane_b32 s20, v249, 6
	s_mov_b64 s[24:25], 0
	s_nop 0
	v_lshl_add_u32 v101, v4, 1, s20
